# P5 epilogue: second batch of x loads issued inside the first batch, ahead of its stores
# speedup vs baseline: 1.0059x; 1.0059x over previous
;     __device__ __forceinline__ void operator()(const f32x4 (&acc)[2][2][4][2], const Unit& u, int wr, int wc, int fr, int fq) const {
;     ...
; #pragma unroll
;         for (int ai = 0; ai < 2; ++ai) {
;             f32x4 xv[4][2][2];
; #pragma unroll
;             for (int m = 0; m < 4; ++m) { const size_t off = (row0 + ai * HALF + m * 16) * 1024 + col0;
; #pragma unroll
;                 for (int bj = 0; bj < 2; ++bj)
; #pragma unroll
;                     for (int n = 0; n < 2; ++n) xv[m][bj][n] = *(const f32x4*)(x + off + bj * HALF + n * 16); }
;             asm volatile("" ::: "memory");
; #pragma unroll
;             for (int m = 0; m < 4; ++m) { const size_t off = (row0 + ai * HALF + m * 16) * 1024 + col0;
; #pragma unroll
;                 for (int bj = 0; bj < 2; ++bj)
; #pragma unroll
;                     for (int n = 0; n < 2; ++n) *(f32x4*)(out + off + bj * HALF + n * 16) = xv[m][bj][n] + gv[bj][n] * acc[ai][bj][m][n]; }
;             asm volatile("" ::: "memory"); }
.LBB0_588:
	s_ashr_i32 s23, s30, 4
	s_ashr_i32 s31, s30, 31
	v_lshl_or_b32 v128, s61, 8, v163
	s_mul_hi_i32 s25, s23, 0x3000
	s_mulk_i32 s23, 0x3000
	s_add_u32 s34, s50, s23
	v_ashrrev_i32_e32 v129, 31, v128
	s_addc_u32 s35, s51, s25
	v_lshlrev_b64 v[232:233], 2, v[128:129]
	s_lshl_b64 s[30:31], s[30:31], 20
	v_lshl_add_u64 v[158:159], s[4:5], 0, v[232:233]
	v_lshl_add_u64 v[234:235], s[30:31], 0, v[148:149]
	v_lshl_add_u64 v[128:129], s[34:35], 0, v[232:233]
	v_lshl_add_u64 v[160:161], v[158:159], 0, v[234:235]
	global_load_dwordx4 v[168:171], v[160:161], off
	global_load_dwordx4 v[140:143], v[128:129], off
	global_load_dwordx4 v[136:139], v[128:129], off offset:64
	global_load_dwordx4 v[172:175], v[160:161], off offset:64
	global_load_dwordx4 v[176:179], v[160:161], off offset:512
	global_load_dwordx4 v[132:135], v[128:129], off offset:512
	s_nop 0
	global_load_dwordx4 v[128:131], v[128:129], off offset:576
	s_nop 0
	global_load_dwordx4 v[180:183], v[160:161], off offset:576
	v_or_b32_e32 v236, 0x10000, v234
	v_mov_b32_e32 v237, v235
	v_or_b32_e32 v238, 0x20000, v234
	v_mov_b32_e32 v239, v235
	v_or_b32_e32 v240, 0x30000, v234
	v_mov_b32_e32 v241, v235
	v_lshl_add_u64 v[196:197], v[158:159], 0, v[236:237]
	v_lshl_add_u64 v[212:213], v[158:159], 0, v[238:239]
	v_lshl_add_u64 v[158:159], v[158:159], 0, v[240:241]
	global_load_dwordx4 v[184:187], v[196:197], off
	global_load_dwordx4 v[188:191], v[196:197], off offset:64
	global_load_dwordx4 v[192:195], v[196:197], off offset:512
	s_nop 0
	global_load_dwordx4 v[196:199], v[196:197], off offset:576
	s_nop 0
	global_load_dwordx4 v[200:203], v[212:213], off
	global_load_dwordx4 v[204:207], v[212:213], off offset:64
	global_load_dwordx4 v[208:211], v[212:213], off offset:512
	s_nop 0
	global_load_dwordx4 v[212:215], v[212:213], off offset:576
	s_nop 0
	global_load_dwordx4 v[216:219], v[158:159], off
	global_load_dwordx4 v[220:223], v[158:159], off offset:64
	global_load_dwordx4 v[224:227], v[158:159], off offset:512
	global_load_dwordx4 v[228:231], v[158:159], off offset:576
	v_lshl_add_u64 v[158:159], s[6:7], 0, v[234:235]
	v_lshl_add_u64 v[158:159], v[158:159], 0, v[232:233]
	v_lshl_add_u64 v[234:235], s[6:7], 0, v[236:237]
	v_lshl_add_u64 v[236:237], s[6:7], 0, v[238:239]
	v_lshl_add_u64 v[238:239], s[6:7], 0, v[240:241]
	v_lshl_add_u64 v[234:235], v[234:235], 0, v[232:233]
	v_lshl_add_u64 v[236:237], v[236:237], 0, v[232:233]
	s_waitcnt vmcnt(0)
	v_pk_fma_f32 v[126:127], v[126:127], v[142:143], v[170:171]
	v_pk_fma_f32 v[124:125], v[124:125], v[140:141], v[168:169]
	v_pk_fma_f32 v[122:123], v[122:123], v[138:139], v[174:175]
	v_pk_fma_f32 v[120:121], v[120:121], v[136:137], v[172:173]
	v_pk_fma_f32 v[106:107], v[106:107], v[134:135], v[178:179]
	v_pk_fma_f32 v[104:105], v[104:105], v[132:133], v[176:177]
	v_pk_fma_f32 v[98:99], v[98:99], v[130:131], v[182:183]
	v_pk_fma_f32 v[96:97], v[96:97], v[128:129], v[180:181]
	v_add_co_u32_e32 v244, vcc, s57, v160
	v_lshl_add_u64 v[246:247], v[160:161], 0, s[14:15]
	s_nop 0
	v_addc_co_u32_e32 v245, vcc, 0, v161, vcc
	global_load_dwordx4 v[168:171], v[244:245], off
	global_load_dwordx4 v[172:175], v[246:247], off offset:64
	global_load_dwordx4 v[176:179], v[246:247], off offset:512
	global_load_dwordx4 v[180:183], v[246:247], off offset:576
	global_store_dwordx4 v[158:159], v[124:127], off
	global_store_dwordx4 v[158:159], v[120:123], off offset:64
	global_store_dwordx4 v[158:159], v[104:107], off offset:512
	global_store_dwordx4 v[158:159], v[96:99], off offset:576
	v_lshl_add_u64 v[242:243], v[158:159], 0, s[16:17]
	s_nop 0
	v_pk_fma_f32 v[98:99], v[118:119], v[142:143], v[186:187]
	v_pk_fma_f32 v[96:97], v[116:117], v[140:141], v[184:185]
	v_pk_fma_f32 v[106:107], v[114:115], v[138:139], v[190:191]
	v_pk_fma_f32 v[80:81], v[80:81], v[132:133], v[208:209]
	v_pk_fma_f32 v[104:105], v[112:113], v[136:137], v[188:189]
	v_pk_fma_f32 v[90:91], v[90:91], v[134:135], v[194:195]
	v_pk_fma_f32 v[88:89], v[88:89], v[132:133], v[192:193]
	v_pk_fma_f32 v[86:87], v[86:87], v[130:131], v[198:199]
	v_pk_fma_f32 v[84:85], v[84:85], v[128:129], v[196:197]
	v_pk_fma_f32 v[110:111], v[110:111], v[142:143], v[202:203]
	v_pk_fma_f32 v[108:109], v[108:109], v[140:141], v[200:201]
	v_pk_fma_f32 v[102:103], v[102:103], v[138:139], v[206:207]
	v_pk_fma_f32 v[100:101], v[100:101], v[136:137], v[204:205]
	v_pk_fma_f32 v[82:83], v[82:83], v[134:135], v[210:211]
	v_pk_fma_f32 v[74:75], v[74:75], v[130:131], v[214:215]
	v_pk_fma_f32 v[72:73], v[72:73], v[128:129], v[212:213]
	v_add_co_u32_e32 v244, vcc, s58, v160
	v_lshl_add_u64 v[246:247], v[160:161], 0, s[16:17]
	s_nop 0
	v_addc_co_u32_e32 v245, vcc, 0, v161, vcc
	v_add_co_u32_e32 v248, vcc, s59, v160
	v_lshl_add_u64 v[250:251], v[160:161], 0, s[18:19]
	s_nop 0
	v_addc_co_u32_e32 v249, vcc, 0, v161, vcc
	global_load_dwordx4 v[184:187], v[244:245], off
	global_load_dwordx4 v[188:191], v[246:247], off offset:64
	global_load_dwordx4 v[192:195], v[246:247], off offset:512
	global_load_dwordx4 v[196:199], v[246:247], off offset:576
	global_load_dwordx4 v[200:203], v[248:249], off
	global_load_dwordx4 v[204:207], v[250:251], off offset:64
	global_load_dwordx4 v[208:211], v[250:251], off offset:512
	global_load_dwordx4 v[212:215], v[250:251], off offset:576
	global_store_dwordx4 v[234:235], v[96:99], off
	global_store_dwordx4 v[234:235], v[104:107], off offset:64
	global_store_dwordx4 v[234:235], v[88:91], off offset:512
	global_store_dwordx4 v[234:235], v[84:87], off offset:576
	global_store_dwordx4 v[236:237], v[108:111], off
	global_store_dwordx4 v[236:237], v[100:103], off offset:64
	global_store_dwordx4 v[236:237], v[80:83], off offset:512
	global_store_dwordx4 v[236:237], v[72:75], off offset:576
	v_pk_fma_f32 v[66:67], v[66:67], v[130:131], v[230:231]
	v_lshl_add_u64 v[80:81], v[238:239], 0, v[232:233]
	v_pk_fma_f32 v[64:65], v[64:65], v[128:129], v[228:229]
	global_store_dwordx4 v[80:81], v[64:67], off offset:576
	v_pk_fma_f32 v[94:95], v[94:95], v[142:143], v[218:219]
	v_pk_fma_f32 v[92:93], v[92:93], v[140:141], v[216:217]
	v_pk_fma_f32 v[74:75], v[78:79], v[138:139], v[222:223]
	v_pk_fma_f32 v[72:73], v[76:77], v[136:137], v[220:221]
	v_pk_fma_f32 v[70:71], v[70:71], v[134:135], v[226:227]
	v_pk_fma_f32 v[68:69], v[68:69], v[132:133], v[224:225]
	v_add_co_u32_e32 v248, vcc, s60, v160
	v_lshl_add_u64 v[250:251], v[160:161], 0, s[20:21]
	s_nop 0
	v_addc_co_u32_e32 v249, vcc, 0, v161, vcc
	global_load_dwordx4 v[216:219], v[248:249], off
	global_load_dwordx4 v[220:223], v[250:251], off offset:64
	global_load_dwordx4 v[224:227], v[250:251], off offset:512
	global_load_dwordx4 v[228:231], v[250:251], off offset:576
	global_store_dwordx4 v[80:81], v[92:95], off
	global_store_dwordx4 v[80:81], v[72:75], off offset:64
	global_store_dwordx4 v[80:81], v[68:71], off offset:512
	v_add_co_u32_e32 v252, vcc, s57, v158
	v_lshl_add_u64 v[160:161], v[158:159], 0, s[14:15]
	s_nop 0
	v_addc_co_u32_e32 v253, vcc, 0, v159, vcc
	v_add_co_u32_e32 v254, vcc, s58, v158
	s_waitcnt vmcnt(31)
;     __device__ __forceinline__ void operator()(const f32x4 (&acc)[2][2][4][2], const Unit& u, int wr, int wc, int fr, int fq) const {
;     ...
; #pragma unroll
;             for (int m = 0; m < 4; ++m) { const size_t off = (row0 + ai * HALF + m * 16) * 1024 + col0;
; #pragma unroll
;                 for (int bj = 0; bj < 2; ++bj)
; #pragma unroll
;                     for (int n = 0; n < 2; ++n) *(f32x4*)(out + off + bj * HALF + n * 16) = xv[m][bj][n] + gv[bj][n] * acc[ai][bj][m][n]; }
;             asm volatile("" ::: "memory"); }
	v_pk_fma_f32 v[62:63], v[62:63], v[142:143], v[170:171]
	v_addc_co_u32_e32 v255, vcc, 0, v159, vcc
	v_pk_fma_f32 v[60:61], v[60:61], v[140:141], v[168:169]
	s_waitcnt vmcnt(30)
	v_pk_fma_f32 v[58:59], v[58:59], v[138:139], v[174:175]
	v_pk_fma_f32 v[56:57], v[56:57], v[136:137], v[172:173]
	s_waitcnt vmcnt(29)
	v_pk_fma_f32 v[46:47], v[46:47], v[134:135], v[178:179]
	s_waitcnt vmcnt(20)
	v_pk_fma_f32 v[30:31], v[30:31], v[130:131], v[198:199]
	v_pk_fma_f32 v[44:45], v[44:45], v[132:133], v[176:177]
	v_pk_fma_f32 v[42:43], v[42:43], v[130:131], v[182:183]
	v_pk_fma_f32 v[40:41], v[40:41], v[128:129], v[180:181]
	v_pk_fma_f32 v[54:55], v[54:55], v[142:143], v[186:187]
	v_pk_fma_f32 v[52:53], v[52:53], v[140:141], v[184:185]
	v_pk_fma_f32 v[50:51], v[50:51], v[138:139], v[190:191]
	v_pk_fma_f32 v[48:49], v[48:49], v[136:137], v[188:189]
	v_pk_fma_f32 v[38:39], v[38:39], v[134:135], v[194:195]
	v_pk_fma_f32 v[36:37], v[36:37], v[132:133], v[192:193]
	v_pk_fma_f32 v[28:29], v[28:29], v[128:129], v[196:197]
	global_store_dwordx4 v[252:253], v[60:63], off
	global_store_dwordx4 v[160:161], v[56:59], off offset:64
	global_store_dwordx4 v[160:161], v[44:47], off offset:512
	global_store_dwordx4 v[160:161], v[40:43], off offset:576
	global_store_dwordx4 v[254:255], v[52:55], off
	global_store_dwordx4 v[242:243], v[48:51], off offset:64
	global_store_dwordx4 v[242:243], v[36:39], off offset:512
	global_store_dwordx4 v[242:243], v[28:31], off offset:576
	s_waitcnt vmcnt(25)
	v_pk_fma_f32 v[18:19], v[18:19], v[134:135], v[210:211]
	v_pk_fma_f32 v[16:17], v[16:17], v[132:133], v[208:209]
	v_pk_fma_f32 v[30:31], v[34:35], v[142:143], v[202:203]
	v_add_co_u32_e32 v34, vcc, s59, v158
	v_pk_fma_f32 v[28:29], v[32:33], v[140:141], v[200:201]
	v_lshl_add_u64 v[32:33], v[158:159], 0, s[18:19]
	v_addc_co_u32_e32 v35, vcc, 0, v159, vcc
	global_store_dwordx4 v[32:33], v[16:19], off offset:512
	s_waitcnt vmcnt(25)
	v_pk_fma_f32 v[14:15], v[14:15], v[130:131], v[214:215]
	v_pk_fma_f32 v[12:13], v[12:13], v[128:129], v[212:213]
	v_add_co_u32_e32 v18, vcc, s60, v158
	v_pk_fma_f32 v[26:27], v[26:27], v[138:139], v[206:207]
	v_pk_fma_f32 v[24:25], v[24:25], v[136:137], v[204:205]
	global_store_dwordx4 v[32:33], v[12:15], off offset:576
	v_lshl_add_u64 v[16:17], v[158:159], 0, s[20:21]
	v_addc_co_u32_e32 v19, vcc, 0, v159, vcc
	s_waitcnt vmcnt(16)
	v_pk_fma_f32 v[14:15], v[22:23], v[142:143], v[218:219]
	v_pk_fma_f32 v[12:13], v[20:21], v[140:141], v[216:217]
	s_waitcnt vmcnt(15)
	v_pk_fma_f32 v[10:11], v[10:11], v[138:139], v[222:223]
	v_pk_fma_f32 v[8:9], v[8:9], v[136:137], v[220:221]
	s_waitcnt vmcnt(14)
	v_pk_fma_f32 v[6:7], v[6:7], v[134:135], v[226:227]
	v_pk_fma_f32 v[4:5], v[4:5], v[132:133], v[224:225]
	s_waitcnt vmcnt(13)
	v_pk_fma_f32 v[2:3], v[2:3], v[130:131], v[230:231]
	v_pk_fma_f32 v[0:1], v[0:1], v[128:129], v[228:229]
	global_store_dwordx4 v[34:35], v[28:31], off
	global_store_dwordx4 v[32:33], v[24:27], off offset:64
	global_store_dwordx4 v[18:19], v[12:15], off
	global_store_dwordx4 v[16:17], v[8:11], off offset:64
	global_store_dwordx4 v[16:17], v[4:7], off offset:512
	global_store_dwordx4 v[16:17], v[0:3], off offset:576
	s_andn2_b64 vcc, exec, s[0:1]
	s_mov_b64 s[0:1], -1
	s_cbranch_vccnz .LBB0_577
	s_andn2_b64 vcc, exec, s[8:9]
	s_cbranch_vccnz .LBB0_576
	s_barrier
	s_branch .LBB0_576
